# NSA fast-path softmax: 32 v_fmamk_f32 replaced by 16 v_pk_fma_f32 (packed f32 instruction selection)
# baseline (speedup 1.0000x reference)
; template <bool FX>
; DI void nsa_tile(const Params& p, int b, int g, int tile, bf16_t* lds, const float CL) {
;     ...
;   for (int hp = 0; hp < 2; ++hp) {
; #pragma unroll
;     for (int hh = 0; hh < 2; ++hh)
; #pragma unroll
;       for (int ks = 0; ks < 2; ++ks) qf[hh][ks] = *(const bf16x8*)(ztok + C_Q + g * 256 + (hp * 2 + hh) * 64 + ks * 32 + quad * 8);
;     st_reset(st);
;     {
;       const bf16_t* kb = zb + C_KS + g * 64;
;       tile64_gload(tid, rk0, rk1, kb, ZS);
;       tile64_gload(tid, rv0, rv1, vsT, TS);
;       for (int s = 0; s <= cur; ++s) {
.LBB0_665:
	s_lshl_b32 s28, s6, 8
	v_lshl_add_u64 v[14:15], v[116:117], 0, s[28:29]
	global_load_dwordx4 v[2:5], v[14:15], off
	global_load_dwordx4 v[6:9], v[14:15], off offset:64
	global_load_dwordx4 v[10:13], v[14:15], off offset:128
	s_nop 0
	global_load_dwordx4 v[14:17], v[14:15], off offset:192
	s_nop 0
	v_and_b32_e32 v202, 7, v196
	v_bfe_u32 v218, v196, 4, 3
	v_xor_b32_e32 v202, v202, v218
	v_lshlrev_b32_e32 v202, 4, v202
	v_mov_b32_e32 v203, 0
	v_sub_u32_e32 v218, v202, v0
	v_ashrrev_i32_e32 v219, 31, v218
	v_readfirstlane_b32 s77, v196
	s_lshr_b32 s76, s77, 8
	s_lshl_b32 s76, s76, 16
	s_bfe_u32 s77, s77, 0x20006
	s_lshl_b32 s77, s77, 10
	s_or_b32 s76, s76, s77
	s_or_b32 s76, s76, 0xc000
	s_mov_b32 s75, 0xc000
	s_movk_i32 s78, 0x600
	s_mov_b32 s79, 0
	v_lshl_add_u64 v[58:59], v[132:133], 0, v[218:219]
	v_lshl_add_u64 v[60:61], v[136:137], 0, v[218:219]
	v_lshl_add_u64 v[62:63], v[140:141], 0, v[218:219]
	v_lshl_add_u64 v[64:65], v[144:145], 0, v[218:219]
	v_lshl_add_u64 v[58:59], v[58:59], 0, s[78:79]
	v_lshl_add_u64 v[60:61], v[60:61], 0, s[78:79]
	s_mov_b32 m0, s76
	s_nop 0
	global_load_lds_dwordx4 v[58:59], off
	s_add_u32 m0, s76, 0x1000
	s_nop 0
	global_load_lds_dwordx4 v[60:61], off
	s_add_u32 m0, s76, 0x2000
	s_nop 0
	global_load_lds_dwordx4 v[62:63], off
	s_add_u32 m0, s76, 0x3000
	s_nop 0
	global_load_lds_dwordx4 v[64:65], off
	s_xor_b32 s76, s76, 0xc000
	s_mov_b32 s86, 0x3fb8aa3b
	s_mov_b32 s87, 0x3fb8aa3b
	v_xor_b32_e32 v188, 0xc000, v188
	v_xor_b32_e32 v189, 0xc000, v189
	v_xor_b32_e32 v190, 0xc000, v190
	v_xor_b32_e32 v191, 0xc000, v191
	v_xor_b32_e32 v207, 0xc000, v207
	v_xor_b32_e32 v208, 0xc000, v208
	v_xor_b32_e32 v209, 0xc000, v209
	v_xor_b32_e32 v210, 0xc000, v210
	v_xor_b32_e32 v211, 0xc000, v211
	v_xor_b32_e32 v212, 0xc000, v212
	v_xor_b32_e32 v213, 0xc000, v213
	v_xor_b32_e32 v214, 0xc000, v214
	v_mov_b32_e32 v54, v1
	v_mov_b32_e32 v55, v1
	v_mov_b32_e32 v56, v1
	v_mov_b32_e32 v57, v1
	v_mov_b64_e32 v[46:47], v[54:55]
	v_mov_b64_e32 v[50:51], v[54:55]
	v_mov_b64_e32 v[42:43], v[54:55]
	v_mov_b64_e32 v[38:39], v[54:55]
	v_mov_b64_e32 v[34:35], v[54:55]
	v_mov_b64_e32 v[30:31], v[54:55]
	v_mov_b64_e32 v[26:27], v[54:55]
	v_mov_b64_e32 v[22:23], v[54:55]
	v_mov_b64_e32 v[18:19], v[54:55]
	s_xor_b64 s[36:37], s[2:3], -1
	s_lshl_b32 s7, s6, 7
	s_mov_b32 s28, 64
	s_mov_b32 s68, -1
	v_mov_b32_e32 v187, v185
	v_lshl_add_u64 v[158:159], v[156:157], 0, v[218:219]
	v_lshl_add_u64 v[160:161], v[154:155], 0, v[218:219]
	v_mov_b64_e32 v[48:49], v[56:57]
	v_mov_b64_e32 v[52:53], v[56:57]
	v_mov_b64_e32 v[44:45], v[56:57]
	v_mov_b64_e32 v[40:41], v[56:57]
	v_mov_b64_e32 v[36:37], v[56:57]
	v_mov_b64_e32 v[32:33], v[56:57]
	v_mov_b64_e32 v[28:29], v[56:57]
	v_mov_b64_e32 v[24:25], v[56:57]
	v_mov_b64_e32 v[20:21], v[56:57]
	s_branch .LBB0_668
; template <int MODE, bool FX>
; DI void attn_compute(const int lane, const bf16_t* Ks, const bf16_t* Vs, const bf16x8 (&qf)[2][2], AttnSt& st, const float (&invl)[2],
;                      int lo, int hi, float (&impA)[4], float (&impE)[4], const float CL) {
;     ...
;   for (int ks = 0; ks < 2; ++ks) {
; #pragma unroll
;     for (int kt = 0; kt < 4; ++kt) {
;       int row = kt * 16 + col;
;       bf16x8 kf = *(const bf16x8*)(Ks + row * 64 + (((ks * 4 + quad) ^ ((row >> 1) & 7)) << 3));
; #pragma unroll
;       for (int hh = 0; hh < 2; ++hh) S[kt][hh] = mfma16(kf, qf[hh][ks], S[kt][hh]);
;     }
;   }
;   bf16x8 pf[2][2];
;   const bool full = (lo <= 0) && (hi >= 63);
;   const bool none = (hi < 0) || (lo > 63) || (hi < lo);
;   if (__all(full || none)) {
;     constexpr float L2E = 1.4426950408889634f;
; #pragma unroll
;     for (int hh = 0; hh < 2; ++hh) {
;       float mL;
;       float il = 1.f;
;       if (FX) {
;         mL = full ? CL : 1e30f;
;         if (MODE == 1) il = invl[hh];
;       } else if (MODE != 1) {
;         float mx = -1e30f;
; #pragma unroll
;         for (int kt = 0; kt < 4; ++kt)
; #pragma unroll
;           for (int j = 0; j < 4; ++j) mx = fmaxf(mx, S[kt][hh][j]);
;         mx = full ? mx : -1e30f;
;         mx = fmaxf(mx, shx(mx, 16, lane));
;         mx = fmaxf(mx, shx(mx, 32, lane));
;         const float m_new = fmaxf(st.m[hh], mx);
;         const float alpha = __expf(st.m[hh] - m_new);
;         st.m[hh] = m_new;
;         st.l[hh] *= alpha;
;         if (MODE == 2) {
; #pragma unroll
;           for (int dt = 0; dt < 4; ++dt) st.O[hh][dt] *= alpha;
;         }
;         mL = full ? m_new * L2E : 1e30f;
;       } else {
;         mL = full ? st.m[hh] * L2E : 1e30f;
;         il = invl[hh];
;       }
;       float rs = 0.f;
; #pragma unroll
;       for (int kt = 0; kt < 4; ++kt) {
;         float a = 0.f;
; #pragma unroll
;         for (int j = 0; j < 4; ++j) {
;           float pv = __builtin_amdgcn_exp2f(fmaf(S[kt][hh][j], L2E, -mL));
;           if (MODE == 1) pv *= il;
;           S[kt][hh][j] = pv;
;           a += pv;
;         }
;         rs += a;
;         if (MODE == 1) {
;           impA[kt] += a;
;           impE[kt] += S[kt][hh][3];
;         }
;       }
;       if (MODE != 1 && !(FX && MODE == 2)) st.l[hh] += rs;
;       if (MODE != 0) {
; #pragma unroll
;         for (int c = 0; c < 2; ++c)
.Lnsa_fast:
	s_waitcnt lgkmcnt(7)
	v_mfma_f32_16x16x32_bf16 v[98:101], v[220:223], v[2:5], 0
	s_waitcnt lgkmcnt(6)
	v_mfma_f32_16x16x32_bf16 v[106:109], v[224:227], v[2:5], 0
	s_waitcnt lgkmcnt(5)
	v_mfma_f32_16x16x32_bf16 v[102:105], v[228:231], v[2:5], 0
	s_waitcnt lgkmcnt(4)
	v_mfma_f32_16x16x32_bf16 v[110:113], v[232:235], v[2:5], 0
	s_waitcnt lgkmcnt(3)
	v_mfma_f32_16x16x32_bf16 v[98:101], v[236:239], v[6:9], v[98:101]
	s_waitcnt lgkmcnt(2)
	v_mfma_f32_16x16x32_bf16 v[106:109], v[240:243], v[6:9], v[106:109]
	s_waitcnt lgkmcnt(1)
	v_mfma_f32_16x16x32_bf16 v[102:105], v[244:247], v[6:9], v[102:105]
	s_waitcnt lgkmcnt(0)
	v_mfma_f32_16x16x32_bf16 v[110:113], v[198:201], v[6:9], v[110:113]
	v_cmp_lt_i32_e32 vcc, 62, v215
	v_mfma_f32_16x16x32_bf16 v[90:93], v[220:223], v[10:13], 0
	v_mfma_f32_16x16x32_bf16 v[94:97], v[224:227], v[10:13], 0
	v_cndmask_b32_e32 v217, v197, v205, vcc
	v_mov_b32_e32 v216, v217
	v_mfma_f32_16x16x32_bf16 v[82:85], v[228:231], v[10:13], 0
	v_mfma_f32_16x16x32_bf16 v[86:89], v[232:235], v[10:13], 0
	v_pk_fma_f32 v[74:75], v[98:99], s[86:87], v[216:217]
	v_mfma_f32_16x16x32_bf16 v[90:93], v[236:239], v[14:17], v[90:93]
	v_pk_fma_f32 v[76:77], v[100:101], s[86:87], v[216:217]
	v_mfma_f32_16x16x32_bf16 v[94:97], v[240:243], v[14:17], v[94:97]
	v_pk_fma_f32 v[78:79], v[106:107], s[86:87], v[216:217]
	v_mfma_f32_16x16x32_bf16 v[82:85], v[244:247], v[14:17], v[82:85]
	v_pk_fma_f32 v[80:81], v[108:109], s[86:87], v[216:217]
	v_mfma_f32_16x16x32_bf16 v[86:89], v[198:201], v[14:17], v[86:89]
	ds_read_b64 v[220:221], v207 offset:8192
	v_pk_fma_f32 v[164:165], v[102:103], s[86:87], v[216:217]
	ds_read_b64 v[222:223], v208 offset:8192
	ds_read_b64 v[224:225], v209 offset:8192
	v_pk_fma_f32 v[166:167], v[104:105], s[86:87], v[216:217]
	ds_read_b64 v[226:227], v210 offset:8192
	ds_read_b64 v[228:229], v207 offset:10240
	v_pk_fma_f32 v[168:169], v[110:111], s[86:87], v[216:217]
	ds_read_b64 v[230:231], v208 offset:10240
	ds_read_b64 v[232:233], v209 offset:10240
	v_pk_fma_f32 v[170:171], v[112:113], s[86:87], v[216:217]
	ds_read_b64 v[234:235], v210 offset:10240
	ds_read_b64 v[236:237], v207 offset:12288
	v_exp_f32_e32 v74, v74
	ds_read_b64 v[238:239], v208 offset:12288
	v_exp_f32_e32 v75, v75
	ds_read_b64 v[240:241], v209 offset:12288
	v_exp_f32_e32 v76, v76
	ds_read_b64 v[242:243], v210 offset:12288
	v_exp_f32_e32 v77, v77
	ds_read_b64 v[244:245], v211 offset:8192
	v_exp_f32_e32 v78, v78
	ds_read_b64 v[246:247], v212 offset:8192
	v_exp_f32_e32 v79, v79
	ds_read_b64 v[198:199], v213 offset:8192
	v_exp_f32_e32 v80, v80
	ds_read_b64 v[200:201], v214 offset:8192
	v_exp_f32_e32 v81, v81
	v_exp_f32_e32 v164, v164
	v_exp_f32_e32 v165, v165
	v_exp_f32_e32 v166, v166
	v_exp_f32_e32 v167, v167
	v_exp_f32_e32 v168, v168
	v_exp_f32_e32 v169, v169
	v_exp_f32_e32 v170, v170
	v_exp_f32_e32 v171, v171
	v_cvt_pk_bf16_f32 v74, v74, v75
	v_cvt_pk_bf16_f32 v75, v76, v77
	v_cvt_pk_bf16_f32 v76, v78, v79
	v_cvt_pk_bf16_f32 v77, v80, v81
	v_cvt_pk_bf16_f32 v78, v164, v165
	v_cvt_pk_bf16_f32 v79, v166, v167
	v_cvt_pk_bf16_f32 v80, v168, v169
	v_cvt_pk_bf16_f32 v81, v170, v171
	s_waitcnt lgkmcnt(0)
	v_pk_fma_f32 v[164:165], v[90:91], s[86:87], v[216:217]
	v_pk_fma_f32 v[166:167], v[92:93], s[86:87], v[216:217]
	v_mfma_f32_16x16x32_bf16 v[50:53], v[220:223], v[74:77], v[50:53]
	s_mov_b32 s10, s8
	s_mov_b32 s11, s8
	s_mov_b32 s9, s8
	v_mfma_f32_16x16x32_bf16 v[42:45], v[228:231], v[74:77], v[42:45]
	v_mov_b64_e32 v[92:93], s[10:11]
	v_mov_b64_e32 v[90:91], s[8:9]
	v_pk_fma_f32 v[168:169], v[94:95], s[86:87], v[216:217]
	v_mfma_f32_16x16x32_bf16 v[38:41], v[236:239], v[74:77], v[38:41]
	v_pk_fma_f32 v[170:171], v[96:97], s[86:87], v[216:217]
	v_pk_fma_f32 v[172:173], v[82:83], s[86:87], v[216:217]
	v_mfma_f32_16x16x32_bf16 v[34:37], v[244:247], v[74:77], v[34:37]
	v_pk_fma_f32 v[174:175], v[84:85], s[86:87], v[216:217]
	v_pk_fma_f32 v[176:177], v[86:87], s[86:87], v[216:217]
	v_mfma_f32_16x16x32_bf16 v[50:53], v[224:227], v[78:81], v[50:53]
	v_pk_fma_f32 v[178:179], v[88:89], s[86:87], v[216:217]
	v_exp_f32_e32 v164, v164
	v_exp_f32_e32 v165, v165
	v_mfma_f32_16x16x32_bf16 v[42:45], v[232:235], v[78:81], v[42:45]
	v_exp_f32_e32 v166, v166
	v_exp_f32_e32 v167, v167
	v_exp_f32_e32 v168, v168
	v_exp_f32_e32 v169, v169
	v_mfma_f32_16x16x32_bf16 v[38:41], v[240:243], v[78:81], v[38:41]
	v_exp_f32_e32 v170, v170
	v_exp_f32_e32 v171, v171
	v_exp_f32_e32 v172, v172
	v_exp_f32_e32 v173, v173
	v_mfma_f32_16x16x32_bf16 v[34:37], v[198:201], v[78:81], v[34:37]
	v_exp_f32_e32 v174, v174
	v_exp_f32_e32 v175, v175
	v_exp_f32_e32 v176, v176
	v_exp_f32_e32 v177, v177
	v_mfma_f32_16x16x32_bf16 v[54:57], v[90:93], v[74:77], v[54:57]
	v_exp_f32_e32 v178, v178
	v_exp_f32_e32 v179, v179
	v_cvt_pk_bf16_f32 v82, v164, v165
	v_cvt_pk_bf16_f32 v83, v166, v167
	v_mfma_f32_16x16x32_bf16 v[54:57], v[90:93], v[78:81], v[54:57]
	v_cvt_pk_bf16_f32 v84, v168, v169
	v_cvt_pk_bf16_f32 v85, v170, v171
	v_cvt_pk_bf16_f32 v86, v172, v173
	v_cvt_pk_bf16_f32 v87, v174, v175
	v_cvt_pk_bf16_f32 v88, v176, v177
	v_cvt_pk_bf16_f32 v89, v178, v179
	s_nop 1
	v_mfma_f32_16x16x32_bf16 v[30:33], v[220:223], v[82:85], v[30:33]
	v_mfma_f32_16x16x32_bf16 v[26:29], v[228:231], v[82:85], v[26:29]
	v_mfma_f32_16x16x32_bf16 v[22:25], v[236:239], v[82:85], v[22:25]
	v_mfma_f32_16x16x32_bf16 v[18:21], v[244:247], v[82:85], v[18:21]
	v_mfma_f32_16x16x32_bf16 v[30:33], v[224:227], v[86:89], v[30:33]
	v_mfma_f32_16x16x32_bf16 v[26:29], v[232:235], v[86:89], v[26:29]
	v_mfma_f32_16x16x32_bf16 v[22:25], v[240:243], v[86:89], v[22:25]
	v_mfma_f32_16x16x32_bf16 v[18:21], v[198:201], v[86:89], v[18:21]
	v_mfma_f32_16x16x32_bf16 v[46:49], v[90:93], v[82:85], v[46:49]
	v_mfma_f32_16x16x32_bf16 v[46:49], v[90:93], v[86:89], v[46:49]
	s_branch .LBB0_667
